# grid barrier: all workgroups poll the top-level generation word; per-XCC generation hop removed
# speedup vs baseline: 1.0083x; 1.0083x over previous
.LBB0_263:
	s_or_b64 exec, exec, s[8:9]
	v_cvt_f32_u32_e32 v4, v2
	s_waitcnt vmcnt(0)
	v_readfirstlane_b32 s6, v3
	v_rcp_iflag_f32_e32 v4, v4
	s_nop 0
	v_add_u32_e32 v1, s6, v1
	v_add_u32_e32 v5, 1, v1
	v_mul_f32_e32 v3, 0x4f7ffffe, v4
	v_cvt_u32_f32_e32 v3, v3
	v_sub_u32_e32 v4, 0, v2
	v_mul_lo_u32 v4, v4, v3
	v_mul_hi_u32 v4, v3, v4
	v_add_u32_e32 v3, v3, v4
	v_mul_hi_u32 v3, v1, v3
	v_mul_lo_u32 v4, v3, v2
	v_sub_u32_e32 v1, v1, v4
	v_add_u32_e32 v6, 1, v3
	v_cmp_ge_u32_e32 vcc, v1, v2
	v_sub_u32_e32 v4, v1, v2
	s_nop 0
	v_cndmask_b32_e32 v3, v3, v6, vcc
	v_cndmask_b32_e32 v1, v1, v4, vcc
	v_add_u32_e32 v4, 1, v3
	v_cmp_ge_u32_e32 vcc, v1, v2
	s_nop 1
	v_cndmask_b32_e32 v1, v3, v4, vcc
	v_mad_u64_u32 v[2:3], s[6:7], v2, v1, v[2:3]
	v_cmp_ne_u32_e32 vcc, v5, v2
	s_and_saveexec_b64 s[6:7], vcc
	s_xor_b64 s[6:7], exec, s[6:7]
	s_cbranch_execz .LBB0_277
	v_mov_b32_e32 v0, 0
	s_add_u32 s12, s0, 0x1caa7a00
	s_addc_u32 s13, s1, 0
	global_load_dword v0, v0, s[12:13] sc1
	s_waitcnt vmcnt(0)
	v_cmp_eq_u32_e32 vcc, v0, v1
	s_and_saveexec_b64 s[8:9], vcc
	s_cbranch_execz .LBB0_276
	s_add_u32 s10, s0, 0x1caa4700
	s_addc_u32 s11, s1, 0
	s_mov_b32 s24, 1
	s_mov_b64 s[14:15], 0
	v_mov_b32_e32 v0, 0
	s_branch .LBB0_267

.LBB0_294:
	s_or_b64 exec, exec, s[0:1]
	s_mov_b64 s[0:1], exec
	v_mbcnt_lo_u32_b32 v0, s0, 0
	v_mbcnt_hi_u32_b32 v0, s1, v0
	v_cmp_eq_u32_e32 vcc, 0, v0
	s_waitcnt vmcnt(0)
	buffer_inv sc1
	s_and_saveexec_b64 s[6:7], vcc
	s_cbranch_execz .LBB0_296
	s_bcnt1_i32_b64 s0, s[0:1]
	v_mov_b32_e32 v0, 0x2000
	v_mov_b32_e32 v1, s0
	s_nop 0

.LBB0_363:
	s_or_b64 exec, exec, s[8:9]
	v_cvt_f32_u32_e32 v4, v2
	s_waitcnt vmcnt(0)
	v_readfirstlane_b32 s6, v3
	v_rcp_iflag_f32_e32 v4, v4
	s_nop 0
	v_add_u32_e32 v1, s6, v1
	v_add_u32_e32 v5, 1, v1
	v_mul_f32_e32 v3, 0x4f7ffffe, v4
	v_cvt_u32_f32_e32 v3, v3
	v_sub_u32_e32 v4, 0, v2
	v_mul_lo_u32 v4, v4, v3
	v_mul_hi_u32 v4, v3, v4
	v_add_u32_e32 v3, v3, v4
	v_mul_hi_u32 v3, v1, v3
	v_mul_lo_u32 v4, v3, v2
	v_sub_u32_e32 v1, v1, v4
	v_add_u32_e32 v6, 1, v3
	v_cmp_ge_u32_e32 vcc, v1, v2
	v_sub_u32_e32 v4, v1, v2
	s_nop 0
	v_cndmask_b32_e32 v3, v3, v6, vcc
	v_cndmask_b32_e32 v1, v1, v4, vcc
	v_add_u32_e32 v4, 1, v3
	v_cmp_ge_u32_e32 vcc, v1, v2
	s_nop 1
	v_cndmask_b32_e32 v1, v3, v4, vcc
	v_mad_u64_u32 v[2:3], s[6:7], v2, v1, v[2:3]
	v_cmp_ne_u32_e32 vcc, v5, v2
	s_and_saveexec_b64 s[6:7], vcc
	s_xor_b64 s[6:7], exec, s[6:7]
	s_cbranch_execz .LBB0_377
	v_mov_b32_e32 v0, 0
	s_add_u32 s12, s2, 0x1caa7a00
	s_addc_u32 s13, s3, 0
	global_load_dword v0, v0, s[12:13] sc1
	s_waitcnt vmcnt(0)
	v_cmp_eq_u32_e32 vcc, v0, v1
	s_and_saveexec_b64 s[8:9], vcc
	s_cbranch_execz .LBB0_376
	s_add_u32 s10, s2, 0x1caa4700
	s_addc_u32 s11, s3, 0
	s_mov_b32 s24, 1
	s_mov_b64 s[14:15], 0
	v_mov_b32_e32 v0, 0
	s_branch .LBB0_367

.LBB0_394:
	s_or_b64 exec, exec, s[2:3]
	s_mov_b64 s[2:3], exec
	v_mbcnt_lo_u32_b32 v0, s2, 0
	v_mbcnt_hi_u32_b32 v0, s3, v0
	v_cmp_eq_u32_e32 vcc, 0, v0
	s_waitcnt vmcnt(0)
	buffer_inv sc1
	s_and_saveexec_b64 s[6:7], vcc
	s_cbranch_execz .LBB0_396
	s_bcnt1_i32_b64 s2, s[2:3]
	v_mov_b32_e32 v0, 0x2000
	v_mov_b32_e32 v1, s2
	s_nop 0

.LBB0_565:
	s_or_b64 exec, exec, s[6:7]
	v_cvt_f32_u32_e32 v4, v2
	s_waitcnt vmcnt(0)
	v_readfirstlane_b32 s4, v3
	v_rcp_iflag_f32_e32 v4, v4
	s_nop 0
	v_add_u32_e32 v1, s4, v1
	v_add_u32_e32 v5, 1, v1
	v_mul_f32_e32 v3, 0x4f7ffffe, v4
	v_cvt_u32_f32_e32 v3, v3
	v_sub_u32_e32 v4, 0, v2
	v_mul_lo_u32 v4, v4, v3
	v_mul_hi_u32 v4, v3, v4
	v_add_u32_e32 v3, v3, v4
	v_mul_hi_u32 v3, v1, v3
	v_mul_lo_u32 v4, v3, v2
	v_sub_u32_e32 v1, v1, v4
	v_add_u32_e32 v6, 1, v3
	v_cmp_ge_u32_e32 vcc, v1, v2
	v_sub_u32_e32 v4, v1, v2
	s_nop 0
	v_cndmask_b32_e32 v3, v3, v6, vcc
	v_cndmask_b32_e32 v1, v1, v4, vcc
	v_add_u32_e32 v4, 1, v3
	v_cmp_ge_u32_e32 vcc, v1, v2
	s_nop 1
	v_cndmask_b32_e32 v1, v3, v4, vcc
	v_mad_u64_u32 v[2:3], s[4:5], v2, v1, v[2:3]
	v_cmp_ne_u32_e32 vcc, v5, v2
	s_and_saveexec_b64 s[4:5], vcc
	s_xor_b64 s[4:5], exec, s[4:5]
	s_cbranch_execz .LBB0_579
	v_mov_b32_e32 v0, 0
	s_add_u32 s12, s8, 0x1caa7a00
	s_addc_u32 s13, s9, 0
	global_load_dword v0, v0, s[12:13] sc1
	s_waitcnt vmcnt(0)
	v_cmp_eq_u32_e32 vcc, v0, v1
	s_and_saveexec_b64 s[6:7], vcc
	s_cbranch_execz .LBB0_578
	s_add_u32 s10, s8, 0x1caa4700
	s_addc_u32 s11, s9, 0
	s_mov_b32 s24, 1
	s_mov_b64 s[14:15], 0
	v_mov_b32_e32 v0, 0
	s_branch .LBB0_569

.LBB0_596:
	s_or_b64 exec, exec, s[4:5]
	s_mov_b64 s[4:5], exec
	v_mbcnt_lo_u32_b32 v0, s4, 0
	v_mbcnt_hi_u32_b32 v0, s5, v0
	v_cmp_eq_u32_e32 vcc, 0, v0
	s_waitcnt vmcnt(0)
	buffer_inv sc1
	s_and_saveexec_b64 s[6:7], vcc
	s_cbranch_execz .LBB0_598
	s_bcnt1_i32_b64 s4, s[4:5]
	v_mov_b32_e32 v0, 0x2000
	v_mov_b32_e32 v1, s4
	s_nop 0

.LBB0_1961:
	s_or_b64 exec, exec, s[8:9]
	v_cvt_f32_u32_e32 v4, v2
	s_waitcnt vmcnt(0)
	v_readfirstlane_b32 s0, v3
	v_rcp_iflag_f32_e32 v4, v4
	s_nop 0
	v_add_u32_e32 v1, s0, v1
	v_add_u32_e32 v5, 1, v1
	v_mul_f32_e32 v3, 0x4f7ffffe, v4
	v_cvt_u32_f32_e32 v3, v3
	v_sub_u32_e32 v4, 0, v2
	v_mul_lo_u32 v4, v4, v3
	v_mul_hi_u32 v4, v3, v4
	v_add_u32_e32 v3, v3, v4
	v_mul_hi_u32 v3, v1, v3
	v_mul_lo_u32 v4, v3, v2
	v_sub_u32_e32 v1, v1, v4
	v_add_u32_e32 v6, 1, v3
	v_cmp_ge_u32_e32 vcc, v1, v2
	v_sub_u32_e32 v4, v1, v2
	s_nop 0
	v_cndmask_b32_e32 v3, v3, v6, vcc
	v_cndmask_b32_e32 v1, v1, v4, vcc
	v_add_u32_e32 v4, 1, v3
	v_cmp_ge_u32_e32 vcc, v1, v2
	s_nop 1
	v_cndmask_b32_e32 v1, v3, v4, vcc
	v_mad_u64_u32 v[2:3], s[0:1], v2, v1, v[2:3]
	v_cmp_ne_u32_e32 vcc, v5, v2
	s_and_saveexec_b64 s[0:1], vcc
	s_xor_b64 s[6:7], exec, s[0:1]
	s_cbranch_execz .LBB0_1975
	v_mov_b32_e32 v0, 0
	s_add_u32 s12, s48, 0x1caa7a00
	s_addc_u32 s13, s49, 0
	global_load_dword v0, v0, s[12:13] sc1
	s_waitcnt vmcnt(0)
	v_cmp_eq_u32_e32 vcc, v0, v1
	s_and_saveexec_b64 s[8:9], vcc
	s_cbranch_execz .LBB0_1974
	s_add_u32 s10, s48, 0x1caa4700
	s_addc_u32 s11, s49, 0
	s_mov_b32 s0, 1
	s_mov_b64 s[14:15], 0
	v_mov_b32_e32 v0, 0
	s_branch .LBB0_1965

.LBB0_2319:
	s_or_b64 exec, exec, s[8:9]
	v_cvt_f32_u32_e32 v4, v2
	s_waitcnt vmcnt(0)
	v_readfirstlane_b32 s6, v3
	v_rcp_iflag_f32_e32 v4, v4
	s_nop 0
	v_add_u32_e32 v1, s6, v1
	v_add_u32_e32 v5, 1, v1
	v_mul_f32_e32 v3, 0x4f7ffffe, v4
	v_cvt_u32_f32_e32 v3, v3
	v_sub_u32_e32 v4, 0, v2
	v_mul_lo_u32 v4, v4, v3
	v_mul_hi_u32 v4, v3, v4
	v_add_u32_e32 v3, v3, v4
	v_mul_hi_u32 v3, v1, v3
	v_mul_lo_u32 v4, v3, v2
	v_sub_u32_e32 v1, v1, v4
	v_add_u32_e32 v6, 1, v3
	v_cmp_ge_u32_e32 vcc, v1, v2
	v_sub_u32_e32 v4, v1, v2
	s_nop 0
	v_cndmask_b32_e32 v3, v3, v6, vcc
	v_cndmask_b32_e32 v1, v1, v4, vcc
	v_add_u32_e32 v4, 1, v3
	v_cmp_ge_u32_e32 vcc, v1, v2
	s_nop 1
	v_cndmask_b32_e32 v1, v3, v4, vcc
	v_mad_u64_u32 v[2:3], s[6:7], v2, v1, v[2:3]
	v_cmp_ne_u32_e32 vcc, v5, v2
	s_and_saveexec_b64 s[6:7], vcc
	s_xor_b64 s[6:7], exec, s[6:7]
	s_cbranch_execz .LBB0_2333
	v_mov_b32_e32 v0, 0
	s_add_u32 s12, s4, 0x1caa7a00
	s_addc_u32 s13, s5, 0
	global_load_dword v0, v0, s[12:13] sc1
	s_waitcnt vmcnt(0)
	v_cmp_eq_u32_e32 vcc, v0, v1
	s_and_saveexec_b64 s[8:9], vcc
	s_cbranch_execz .LBB0_2332
	s_add_u32 s10, s4, 0x1caa4700
	s_addc_u32 s11, s5, 0
	s_mov_b32 s24, 1
	s_mov_b64 s[14:15], 0
	v_mov_b32_e32 v0, 0
	s_branch .LBB0_2323
